# FFN-up SwiGLU epilogue rewritten by hand (r^2 folded into the reciprocal, running row pointer, 3-stage row pipeline); setprio mid-pairs removed
# baseline (speedup 1.0000x reference)
; #define LAS __attribute__((address_space(3)))
; __device__ __forceinline__ unsigned cvt_pk2(float lo, float hi) { f32x2c v = {lo, hi}; bf16x2c q = __builtin_convertvector(v, bf16x2c); return __builtin_bit_cast(unsigned, q); }
;     __device__ __forceinline__ void operator()(const f32x4 (&acc)[2][2][4][2], const pg8::Unit& u, int wr, int wc, int fr, int fq) const {
;         const int row0 = u.pm * 256 + wr * 64 + fr, col0 = u.pn * 128 + wc * 32 + 8 * fq;
;         const LAS float* rt = rt_.of(u.pm) + wr * 64 + fr;
; #pragma unroll
;         for (int ai = 0; ai < 2; ++ai)
; #pragma unroll
;             for (int m = 0; m < 4; ++m) { bf16_t* rowp = O + (size_t)(row0 + ai * 128 + m * 16) * FF + col0; const float r = rt[ai * 128 + m * 16];
;                 const float rl = -r * LOG2E, r2 = r * r; unsigned w[4];
; #pragma unroll
;                 for (int n = 0; n < 2; ++n)
; #pragma unroll
;                     for (int h = 0; h < 2; ++h) { const f32x2v g = {acc[ai][0][m][n][2 * h], acc[ai][0][m][n][2 * h + 1]}, uu = {acc[ai][1][m][n][2 * h], acc[ai][1][m][n][2 * h + 1]};
;                         const f32x2v t = g * rl; f32x2v d = {__builtin_amdgcn_exp2f(t.x), __builtin_amdgcn_exp2f(t.y)}; d = d + 1.0f;
;                         const f32x2v q = {__builtin_amdgcn_rcpf(d.x), __builtin_amdgcn_rcpf(d.y)}; const f32x2v o = ((g * uu) * r2) * q;
;                         w[2 * n + h] = cvt_pk2(o.x, o.y); }
;                 u32x4 wv; wv.x = w[0]; wv.y = w[1]; wv.z = w[2]; wv.w = w[3];
;                 *(u32x4*)rowp = wv; }
.LBB0_227:
	s_cmp_eq_u32 s34, s51
	s_cselect_b32 s13, s65, 0x300
	s_cmp_lg_u32 s34, s52
	s_cselect_b32 s13, s13, 0x100
	s_cmp_lg_u32 s34, s50
	s_cselect_b32 s13, s13, 0
	v_lshl_add_u32 v154, s13, 2, v148
	ds_read2_b32 v[200:201], v154 offset1:16
	ds_read2_b32 v[202:203], v154 offset0:32 offset1:48
	ds_read2_b32 v[204:205], v154 offset0:128 offset1:144
	ds_read2_b32 v[206:207], v154 offset0:160 offset1:176
	v_lshl_add_u32 v153, s34, 8, v146
	v_lshl_or_b32 v158, s67, 7, v149
	v_mov_b64_e32 v[178:179], s[40:41]
	s_mov_b32 s98, 0x1600
	v_lshlrev_b32_e32 v158, 1, v158
	v_mov_b32_e32 v159, 0
	v_mad_i64_i32 v[178:179], s[20:21], v153, s98, v[178:179]
	s_mov_b32 s98, 0x16000
	s_mov_b32 s99, 0
	s_mov_b32 s100, 0x6e000
	s_mov_b32 s101, 0
	v_lshl_add_u64 v[178:179], v[178:179], 0, v[158:159]
	s_waitcnt lgkmcnt(0)
	v_mul_f32_e32 v208, 0xbfb8aa3b, v200
	v_mul_f32_e32 v228, v200, v200
	v_mul_f32_e32 v210, 0xbfb8aa3b, v201
	v_mul_f32_e32 v230, v201, v201
	v_mul_f32_e32 v212, 0xbfb8aa3b, v202
	v_mul_f32_e32 v232, v202, v202
	v_mul_f32_e32 v214, 0xbfb8aa3b, v203
	v_mul_f32_e32 v234, v203, v203
	v_mul_f32_e32 v216, 0xbfb8aa3b, v204
	v_mul_f32_e32 v236, v204, v204
	v_mul_f32_e32 v218, 0xbfb8aa3b, v205
	v_mul_f32_e32 v238, v205, v205
	v_mul_f32_e32 v220, 0xbfb8aa3b, v206
	v_mul_f32_e32 v240, v206, v206
	v_mul_f32_e32 v222, 0xbfb8aa3b, v207
	v_mul_f32_e32 v242, v207, v207
	v_rcp_f32_e32 v228, v228
	v_rcp_f32_e32 v230, v230
	v_rcp_f32_e32 v232, v232
	v_rcp_f32_e32 v234, v234
	v_rcp_f32_e32 v236, v236
	v_rcp_f32_e32 v238, v238
	v_rcp_f32_e32 v240, v240
	v_rcp_f32_e32 v242, v242
	v_pk_mul_f32 v[154:155], v[124:125], v[208:209] op_sel_hi:[1,0]
	v_pk_mul_f32 v[156:157], v[126:127], v[208:209] op_sel_hi:[1,0]
	v_pk_mul_f32 v[158:159], v[116:117], v[208:209] op_sel_hi:[1,0]
	v_pk_mul_f32 v[160:161], v[118:119], v[208:209] op_sel_hi:[1,0]
	v_exp_f32_e32 v154, v154
	v_exp_f32_e32 v155, v155
	v_exp_f32_e32 v156, v156
	v_exp_f32_e32 v157, v157
	v_exp_f32_e32 v158, v158
	v_exp_f32_e32 v159, v159
	v_exp_f32_e32 v160, v160
	v_exp_f32_e32 v161, v161
	v_pk_mul_f32 v[162:163], v[108:109], v[210:211] op_sel_hi:[1,0]
	v_pk_mul_f32 v[164:165], v[110:111], v[210:211] op_sel_hi:[1,0]
	v_pk_mul_f32 v[166:167], v[100:101], v[210:211] op_sel_hi:[1,0]
	v_pk_mul_f32 v[168:169], v[102:103], v[210:211] op_sel_hi:[1,0]
	v_exp_f32_e32 v162, v162
	v_exp_f32_e32 v163, v163
	v_exp_f32_e32 v164, v164
	v_exp_f32_e32 v165, v165
	v_exp_f32_e32 v166, v166
	v_exp_f32_e32 v167, v167
	v_exp_f32_e32 v168, v168
	v_exp_f32_e32 v169, v169
	v_pk_mul_f32 v[120:121], v[124:125], v[120:121]
	v_pk_mul_f32 v[122:123], v[126:127], v[122:123]
	v_pk_mul_f32 v[112:113], v[116:117], v[112:113]
	v_pk_mul_f32 v[114:115], v[118:119], v[114:115]
	v_pk_fma_f32 v[154:155], v[154:155], v[228:229], v[228:229] op_sel_hi:[1,0,0]
	v_pk_fma_f32 v[156:157], v[156:157], v[228:229], v[228:229] op_sel_hi:[1,0,0]
	v_pk_fma_f32 v[158:159], v[158:159], v[228:229], v[228:229] op_sel_hi:[1,0,0]
	v_pk_fma_f32 v[160:161], v[160:161], v[228:229], v[228:229] op_sel_hi:[1,0,0]
	v_rcp_f32_e32 v154, v154
	v_rcp_f32_e32 v155, v155
	v_rcp_f32_e32 v156, v156
	v_rcp_f32_e32 v157, v157
	v_rcp_f32_e32 v158, v158
	v_rcp_f32_e32 v159, v159
	v_rcp_f32_e32 v160, v160
	v_rcp_f32_e32 v161, v161
	v_pk_mul_f32 v[170:171], v[92:93], v[212:213] op_sel_hi:[1,0]
	v_pk_mul_f32 v[172:173], v[94:95], v[212:213] op_sel_hi:[1,0]
	v_pk_mul_f32 v[174:175], v[84:85], v[212:213] op_sel_hi:[1,0]
	v_pk_mul_f32 v[176:177], v[86:87], v[212:213] op_sel_hi:[1,0]
	v_exp_f32_e32 v170, v170
	v_exp_f32_e32 v171, v171
	v_exp_f32_e32 v172, v172
	v_exp_f32_e32 v173, v173
	v_exp_f32_e32 v174, v174
	v_exp_f32_e32 v175, v175
	v_exp_f32_e32 v176, v176
	v_exp_f32_e32 v177, v177
	v_pk_mul_f32 v[104:105], v[108:109], v[104:105]
	v_pk_mul_f32 v[106:107], v[110:111], v[106:107]
	v_pk_mul_f32 v[96:97], v[100:101], v[96:97]
	v_pk_mul_f32 v[98:99], v[102:103], v[98:99]
	v_pk_fma_f32 v[162:163], v[162:163], v[230:231], v[230:231] op_sel_hi:[1,0,0]
	v_pk_fma_f32 v[164:165], v[164:165], v[230:231], v[230:231] op_sel_hi:[1,0,0]
	v_pk_fma_f32 v[166:167], v[166:167], v[230:231], v[230:231] op_sel_hi:[1,0,0]
	v_pk_fma_f32 v[168:169], v[168:169], v[230:231], v[230:231] op_sel_hi:[1,0,0]
	v_rcp_f32_e32 v162, v162
	v_rcp_f32_e32 v163, v163
	v_rcp_f32_e32 v164, v164
	v_rcp_f32_e32 v165, v165
	v_rcp_f32_e32 v166, v166
	v_rcp_f32_e32 v167, v167
	v_rcp_f32_e32 v168, v168
	v_rcp_f32_e32 v169, v169
	v_pk_mul_f32 v[120:121], v[120:121], v[154:155]
	v_pk_mul_f32 v[122:123], v[122:123], v[156:157]
	v_pk_mul_f32 v[112:113], v[112:113], v[158:159]
	v_pk_mul_f32 v[114:115], v[114:115], v[160:161]
	v_cvt_pk_bf16_f32 v154, v120, v121
	v_cvt_pk_bf16_f32 v155, v122, v123
	v_cvt_pk_bf16_f32 v156, v112, v113
	v_cvt_pk_bf16_f32 v157, v114, v115
	global_store_dwordx4 v[178:179], v[154:157], off
	v_lshl_add_u64 v[178:179], v[178:179], 0, s[98:99]
	s_nop 1
	v_pk_mul_f32 v[154:155], v[76:77], v[214:215] op_sel_hi:[1,0]
	v_pk_mul_f32 v[156:157], v[78:79], v[214:215] op_sel_hi:[1,0]
	v_pk_mul_f32 v[158:159], v[68:69], v[214:215] op_sel_hi:[1,0]
	v_pk_mul_f32 v[160:161], v[70:71], v[214:215] op_sel_hi:[1,0]
	v_exp_f32_e32 v154, v154
	v_exp_f32_e32 v155, v155
	v_exp_f32_e32 v156, v156
	v_exp_f32_e32 v157, v157
	v_exp_f32_e32 v158, v158
	v_exp_f32_e32 v159, v159
	v_exp_f32_e32 v160, v160
	v_exp_f32_e32 v161, v161
	v_pk_mul_f32 v[88:89], v[92:93], v[88:89]
	v_pk_mul_f32 v[90:91], v[94:95], v[90:91]
	v_pk_mul_f32 v[80:81], v[84:85], v[80:81]
	v_pk_mul_f32 v[82:83], v[86:87], v[82:83]
	v_pk_fma_f32 v[170:171], v[170:171], v[232:233], v[232:233] op_sel_hi:[1,0,0]
	v_pk_fma_f32 v[172:173], v[172:173], v[232:233], v[232:233] op_sel_hi:[1,0,0]
; __device__ __forceinline__ unsigned cvt_pk2(float lo, float hi) { f32x2c v = {lo, hi}; bf16x2c q = __builtin_convertvector(v, bf16x2c); return __builtin_bit_cast(unsigned, q); }
;     __device__ __forceinline__ void operator()(const f32x4 (&acc)[2][2][4][2], const pg8::Unit& u, int wr, int wc, int fr, int fq) const {
;     ...
;             for (int m = 0; m < 4; ++m) { bf16_t* rowp = O + (size_t)(row0 + ai * 128 + m * 16) * FF + col0; const float r = rt[ai * 128 + m * 16];
;                 const float rl = -r * LOG2E, r2 = r * r; unsigned w[4];
; #pragma unroll
;                 for (int n = 0; n < 2; ++n)
; #pragma unroll
;                     for (int h = 0; h < 2; ++h) { const f32x2v g = {acc[ai][0][m][n][2 * h], acc[ai][0][m][n][2 * h + 1]}, uu = {acc[ai][1][m][n][2 * h], acc[ai][1][m][n][2 * h + 1]};
;                         const f32x2v t = g * rl; f32x2v d = {__builtin_amdgcn_exp2f(t.x), __builtin_amdgcn_exp2f(t.y)}; d = d + 1.0f;
;                         const f32x2v q = {__builtin_amdgcn_rcpf(d.x), __builtin_amdgcn_rcpf(d.y)}; const f32x2v o = ((g * uu) * r2) * q;
;                         w[2 * n + h] = cvt_pk2(o.x, o.y); }
;                 u32x4 wv; wv.x = w[0]; wv.y = w[1]; wv.z = w[2]; wv.w = w[3];
;                 *(u32x4*)rowp = wv; }
	v_pk_fma_f32 v[174:175], v[174:175], v[232:233], v[232:233] op_sel_hi:[1,0,0]
	v_pk_fma_f32 v[176:177], v[176:177], v[232:233], v[232:233] op_sel_hi:[1,0,0]
	v_rcp_f32_e32 v170, v170
	v_rcp_f32_e32 v171, v171
	v_rcp_f32_e32 v172, v172
	v_rcp_f32_e32 v173, v173
	v_rcp_f32_e32 v174, v174
	v_rcp_f32_e32 v175, v175
	v_rcp_f32_e32 v176, v176
	v_rcp_f32_e32 v177, v177
	v_pk_mul_f32 v[104:105], v[104:105], v[162:163]
	v_pk_mul_f32 v[106:107], v[106:107], v[164:165]
	v_pk_mul_f32 v[96:97], v[96:97], v[166:167]
	v_pk_mul_f32 v[98:99], v[98:99], v[168:169]
	v_cvt_pk_bf16_f32 v162, v104, v105
	v_cvt_pk_bf16_f32 v163, v106, v107
	v_cvt_pk_bf16_f32 v164, v96, v97
	v_cvt_pk_bf16_f32 v165, v98, v99
	global_store_dwordx4 v[178:179], v[162:165], off
	v_lshl_add_u64 v[178:179], v[178:179], 0, s[98:99]
	s_nop 1
	v_pk_mul_f32 v[162:163], v[60:61], v[216:217] op_sel_hi:[1,0]
	v_pk_mul_f32 v[164:165], v[62:63], v[216:217] op_sel_hi:[1,0]
	v_pk_mul_f32 v[166:167], v[52:53], v[216:217] op_sel_hi:[1,0]
	v_pk_mul_f32 v[168:169], v[54:55], v[216:217] op_sel_hi:[1,0]
	v_exp_f32_e32 v162, v162
	v_exp_f32_e32 v163, v163
	v_exp_f32_e32 v164, v164
	v_exp_f32_e32 v165, v165
	v_exp_f32_e32 v166, v166
	v_exp_f32_e32 v167, v167
	v_exp_f32_e32 v168, v168
	v_exp_f32_e32 v169, v169
	v_pk_mul_f32 v[72:73], v[76:77], v[72:73]
	v_pk_mul_f32 v[74:75], v[78:79], v[74:75]
	v_pk_mul_f32 v[64:65], v[68:69], v[64:65]
	v_pk_mul_f32 v[66:67], v[70:71], v[66:67]
	v_pk_fma_f32 v[154:155], v[154:155], v[234:235], v[234:235] op_sel_hi:[1,0,0]
	v_pk_fma_f32 v[156:157], v[156:157], v[234:235], v[234:235] op_sel_hi:[1,0,0]
	v_pk_fma_f32 v[158:159], v[158:159], v[234:235], v[234:235] op_sel_hi:[1,0,0]
	v_pk_fma_f32 v[160:161], v[160:161], v[234:235], v[234:235] op_sel_hi:[1,0,0]
	v_rcp_f32_e32 v154, v154
	v_rcp_f32_e32 v155, v155
	v_rcp_f32_e32 v156, v156
	v_rcp_f32_e32 v157, v157
	v_rcp_f32_e32 v158, v158
	v_rcp_f32_e32 v159, v159
	v_rcp_f32_e32 v160, v160
	v_rcp_f32_e32 v161, v161
	v_pk_mul_f32 v[88:89], v[88:89], v[170:171]
	v_pk_mul_f32 v[90:91], v[90:91], v[172:173]
	v_pk_mul_f32 v[80:81], v[80:81], v[174:175]
	v_pk_mul_f32 v[82:83], v[82:83], v[176:177]
	v_cvt_pk_bf16_f32 v170, v88, v89
	v_cvt_pk_bf16_f32 v171, v90, v91
	v_cvt_pk_bf16_f32 v172, v80, v81
	v_cvt_pk_bf16_f32 v173, v82, v83
	global_store_dwordx4 v[178:179], v[170:173], off
	v_lshl_add_u64 v[178:179], v[178:179], 0, s[98:99]
	s_nop 1
	v_pk_mul_f32 v[170:171], v[44:45], v[218:219] op_sel_hi:[1,0]
	v_pk_mul_f32 v[172:173], v[46:47], v[218:219] op_sel_hi:[1,0]
	v_pk_mul_f32 v[174:175], v[36:37], v[218:219] op_sel_hi:[1,0]
	v_pk_mul_f32 v[176:177], v[38:39], v[218:219] op_sel_hi:[1,0]
	v_exp_f32_e32 v170, v170
	v_exp_f32_e32 v171, v171
	v_exp_f32_e32 v172, v172
	v_exp_f32_e32 v173, v173
	v_exp_f32_e32 v174, v174
	v_exp_f32_e32 v175, v175
	v_exp_f32_e32 v176, v176
	v_exp_f32_e32 v177, v177
	v_pk_mul_f32 v[56:57], v[60:61], v[56:57]
	v_pk_mul_f32 v[58:59], v[62:63], v[58:59]
	v_pk_mul_f32 v[48:49], v[52:53], v[48:49]
	v_pk_mul_f32 v[50:51], v[54:55], v[50:51]
	v_pk_fma_f32 v[162:163], v[162:163], v[236:237], v[236:237] op_sel_hi:[1,0,0]
	v_pk_fma_f32 v[164:165], v[164:165], v[236:237], v[236:237] op_sel_hi:[1,0,0]
	v_pk_fma_f32 v[166:167], v[166:167], v[236:237], v[236:237] op_sel_hi:[1,0,0]
	v_pk_fma_f32 v[168:169], v[168:169], v[236:237], v[236:237] op_sel_hi:[1,0,0]
	v_rcp_f32_e32 v162, v162
	v_rcp_f32_e32 v163, v163
	v_rcp_f32_e32 v164, v164
	v_rcp_f32_e32 v165, v165
	v_rcp_f32_e32 v166, v166
	v_rcp_f32_e32 v167, v167
	v_rcp_f32_e32 v168, v168
	v_rcp_f32_e32 v169, v169
	v_pk_mul_f32 v[72:73], v[72:73], v[154:155]
	v_pk_mul_f32 v[74:75], v[74:75], v[156:157]
	v_pk_mul_f32 v[64:65], v[64:65], v[158:159]
	v_pk_mul_f32 v[66:67], v[66:67], v[160:161]
	v_cvt_pk_bf16_f32 v154, v72, v73
	v_cvt_pk_bf16_f32 v155, v74, v75
	v_cvt_pk_bf16_f32 v156, v64, v65
	v_cvt_pk_bf16_f32 v157, v66, v67
	global_store_dwordx4 v[178:179], v[154:157], off
	v_lshl_add_u64 v[178:179], v[178:179], 0, s[100:101]
	s_nop 1
	v_pk_mul_f32 v[154:155], v[28:29], v[220:221] op_sel_hi:[1,0]
	v_pk_mul_f32 v[156:157], v[30:31], v[220:221] op_sel_hi:[1,0]
	v_pk_mul_f32 v[158:159], v[20:21], v[220:221] op_sel_hi:[1,0]
	v_pk_mul_f32 v[160:161], v[22:23], v[220:221] op_sel_hi:[1,0]
	v_exp_f32_e32 v154, v154
	v_exp_f32_e32 v155, v155
	v_exp_f32_e32 v156, v156
	v_exp_f32_e32 v157, v157
	v_exp_f32_e32 v158, v158
	v_exp_f32_e32 v159, v159
; #define PG8_BAR __builtin_amdgcn_s_barrier()
; __device__ __forceinline__ unsigned cvt_pk2(float lo, float hi) { f32x2c v = {lo, hi}; bf16x2c q = __builtin_convertvector(v, bf16x2c); return __builtin_bit_cast(unsigned, q); }
; template <class Epi, class Sched, bool ALIGN_EPI = false, bool SP2 = false>
; __device__ __forceinline__ void gemm_phase(PG8_LAS unsigned char* lds, const Gemm g, const Sched& S, const Epi& E) {
;     ...
;         if (!has_next) break;
; #pragma unroll
;         for (int a = 0; a < 2; ++a)
; #pragma unroll
;             for (int b = 0; b < 2; ++b)
; #pragma unroll
;                 for (int m = 0; m < 4; ++m)
; #pragma unroll
;                     for (int n = 0; n < 2; ++n) acc[a][b][m][n] = (f32x4){0.f, 0.f, 0.f, 0.f};
;         cur = nxt; cA = nA; cB = nB; ++ui;
;         if constexpr (ALIGN_EPI) { if (wr == 1) PG8_BAR; }
;     __device__ __forceinline__ void operator()(const f32x4 (&acc)[2][2][4][2], const pg8::Unit& u, int wr, int wc, int fr, int fq) const {
;     ...
;             for (int m = 0; m < 4; ++m) { bf16_t* rowp = O + (size_t)(row0 + ai * 128 + m * 16) * FF + col0; const float r = rt[ai * 128 + m * 16];
;                 const float rl = -r * LOG2E, r2 = r * r; unsigned w[4];
; #pragma unroll
;                 for (int n = 0; n < 2; ++n)
; #pragma unroll
;                     for (int h = 0; h < 2; ++h) { const f32x2v g = {acc[ai][0][m][n][2 * h], acc[ai][0][m][n][2 * h + 1]}, uu = {acc[ai][1][m][n][2 * h], acc[ai][1][m][n][2 * h + 1]};
;                         const f32x2v t = g * rl; f32x2v d = {__builtin_amdgcn_exp2f(t.x), __builtin_amdgcn_exp2f(t.y)}; d = d + 1.0f;
;                         const f32x2v q = {__builtin_amdgcn_rcpf(d.x), __builtin_amdgcn_rcpf(d.y)}; const f32x2v o = ((g * uu) * r2) * q;
;                         w[2 * n + h] = cvt_pk2(o.x, o.y); }
;                 u32x4 wv; wv.x = w[0]; wv.y = w[1]; wv.z = w[2]; wv.w = w[3];
;                 *(u32x4*)rowp = wv; }
	v_exp_f32_e32 v160, v160
	v_exp_f32_e32 v161, v161
	v_pk_mul_f32 v[40:41], v[44:45], v[40:41]
	v_pk_mul_f32 v[42:43], v[46:47], v[42:43]
	v_pk_mul_f32 v[32:33], v[36:37], v[32:33]
	v_pk_mul_f32 v[34:35], v[38:39], v[34:35]
	v_pk_fma_f32 v[170:171], v[170:171], v[238:239], v[238:239] op_sel_hi:[1,0,0]
	v_pk_fma_f32 v[172:173], v[172:173], v[238:239], v[238:239] op_sel_hi:[1,0,0]
	v_pk_fma_f32 v[174:175], v[174:175], v[238:239], v[238:239] op_sel_hi:[1,0,0]
	v_pk_fma_f32 v[176:177], v[176:177], v[238:239], v[238:239] op_sel_hi:[1,0,0]
	v_rcp_f32_e32 v170, v170
	v_rcp_f32_e32 v171, v171
	v_rcp_f32_e32 v172, v172
	v_rcp_f32_e32 v173, v173
	v_rcp_f32_e32 v174, v174
	v_rcp_f32_e32 v175, v175
	v_rcp_f32_e32 v176, v176
	v_rcp_f32_e32 v177, v177
	v_pk_mul_f32 v[56:57], v[56:57], v[162:163]
	v_pk_mul_f32 v[58:59], v[58:59], v[164:165]
	v_pk_mul_f32 v[48:49], v[48:49], v[166:167]
	v_pk_mul_f32 v[50:51], v[50:51], v[168:169]
	v_cvt_pk_bf16_f32 v162, v56, v57
	v_cvt_pk_bf16_f32 v163, v58, v59
	v_cvt_pk_bf16_f32 v164, v48, v49
	v_cvt_pk_bf16_f32 v165, v50, v51
	global_store_dwordx4 v[178:179], v[162:165], off
	v_lshl_add_u64 v[178:179], v[178:179], 0, s[98:99]
	s_nop 1
	v_pk_mul_f32 v[162:163], v[12:13], v[222:223] op_sel_hi:[1,0]
	v_pk_mul_f32 v[164:165], v[14:15], v[222:223] op_sel_hi:[1,0]
	v_pk_mul_f32 v[166:167], v[4:5], v[222:223] op_sel_hi:[1,0]
	v_pk_mul_f32 v[168:169], v[6:7], v[222:223] op_sel_hi:[1,0]
	v_exp_f32_e32 v162, v162
	v_exp_f32_e32 v163, v163
	v_exp_f32_e32 v164, v164
	v_exp_f32_e32 v165, v165
	v_exp_f32_e32 v166, v166
	v_exp_f32_e32 v167, v167
	v_exp_f32_e32 v168, v168
	v_exp_f32_e32 v169, v169
	v_pk_mul_f32 v[24:25], v[28:29], v[24:25]
	v_pk_mul_f32 v[26:27], v[30:31], v[26:27]
	v_pk_mul_f32 v[16:17], v[20:21], v[16:17]
	v_pk_mul_f32 v[18:19], v[22:23], v[18:19]
	v_pk_fma_f32 v[154:155], v[154:155], v[240:241], v[240:241] op_sel_hi:[1,0,0]
	v_pk_fma_f32 v[156:157], v[156:157], v[240:241], v[240:241] op_sel_hi:[1,0,0]
	v_pk_fma_f32 v[158:159], v[158:159], v[240:241], v[240:241] op_sel_hi:[1,0,0]
	v_pk_fma_f32 v[160:161], v[160:161], v[240:241], v[240:241] op_sel_hi:[1,0,0]
	v_rcp_f32_e32 v154, v154
	v_rcp_f32_e32 v155, v155
	v_rcp_f32_e32 v156, v156
	v_rcp_f32_e32 v157, v157
	v_rcp_f32_e32 v158, v158
	v_rcp_f32_e32 v159, v159
	v_rcp_f32_e32 v160, v160
	v_rcp_f32_e32 v161, v161
	v_pk_mul_f32 v[40:41], v[40:41], v[170:171]
	v_pk_mul_f32 v[42:43], v[42:43], v[172:173]
	v_pk_mul_f32 v[32:33], v[32:33], v[174:175]
	v_pk_mul_f32 v[34:35], v[34:35], v[176:177]
	v_cvt_pk_bf16_f32 v170, v40, v41
	v_cvt_pk_bf16_f32 v171, v42, v43
	v_cvt_pk_bf16_f32 v172, v32, v33
	v_cvt_pk_bf16_f32 v173, v34, v35
	global_store_dwordx4 v[178:179], v[170:173], off
	v_lshl_add_u64 v[178:179], v[178:179], 0, s[98:99]
	s_nop 1
	v_pk_mul_f32 v[8:9], v[12:13], v[8:9]
	v_pk_mul_f32 v[10:11], v[14:15], v[10:11]
	v_pk_mul_f32 v[0:1], v[4:5], v[0:1]
	v_pk_mul_f32 v[2:3], v[6:7], v[2:3]
	v_pk_fma_f32 v[162:163], v[162:163], v[242:243], v[242:243] op_sel_hi:[1,0,0]
	v_pk_fma_f32 v[164:165], v[164:165], v[242:243], v[242:243] op_sel_hi:[1,0,0]
	v_pk_fma_f32 v[166:167], v[166:167], v[242:243], v[242:243] op_sel_hi:[1,0,0]
	v_pk_fma_f32 v[168:169], v[168:169], v[242:243], v[242:243] op_sel_hi:[1,0,0]
	v_rcp_f32_e32 v162, v162
	v_rcp_f32_e32 v163, v163
	v_rcp_f32_e32 v164, v164
	v_rcp_f32_e32 v165, v165
	v_rcp_f32_e32 v166, v166
	v_rcp_f32_e32 v167, v167
	v_rcp_f32_e32 v168, v168
	v_rcp_f32_e32 v169, v169
	v_pk_mul_f32 v[24:25], v[24:25], v[154:155]
	v_pk_mul_f32 v[26:27], v[26:27], v[156:157]
	v_pk_mul_f32 v[16:17], v[16:17], v[158:159]
	v_pk_mul_f32 v[18:19], v[18:19], v[160:161]
	v_cvt_pk_bf16_f32 v154, v24, v25
	v_cvt_pk_bf16_f32 v155, v26, v27
	v_cvt_pk_bf16_f32 v156, v16, v17
	v_cvt_pk_bf16_f32 v157, v18, v19
	global_store_dwordx4 v[178:179], v[154:157], off
	v_lshl_add_u64 v[178:179], v[178:179], 0, s[98:99]
	s_nop 1
	v_pk_mul_f32 v[8:9], v[8:9], v[162:163]
	v_pk_mul_f32 v[10:11], v[10:11], v[164:165]
	v_pk_mul_f32 v[0:1], v[0:1], v[166:167]
	v_pk_mul_f32 v[2:3], v[2:3], v[168:169]
	v_cvt_pk_bf16_f32 v162, v8, v9
	v_cvt_pk_bf16_f32 v163, v10, v11
	v_cvt_pk_bf16_f32 v164, v0, v1
	v_cvt_pk_bf16_f32 v165, v2, v3
	global_store_dwordx4 v[178:179], v[162:165], off
	s_andn2_b64 vcc, exec, s[4:5]
	s_mov_b64 s[4:5], -1
	s_cbranch_vccnz .LBB0_220
	s_andn2_b64 vcc, exec, s[0:1]
	s_cbranch_vccnz .LBB0_219
	s_barrier
	s_branch .LBB0_219

; #define LAS __attribute__((address_space(3)))
; __device__ __forceinline__ unsigned cvt_pk2(float lo, float hi) { f32x2c v = {lo, hi}; bf16x2c q = __builtin_convertvector(v, bf16x2c); return __builtin_bit_cast(unsigned, q); }
;     __device__ __forceinline__ void operator()(const f32x4 (&acc)[2][2][4][2], const pg8::Unit& u, int wr, int wc, int fr, int fq) const {
;         const int row0 = u.pm * 256 + wr * 64 + fr, col0 = u.pn * 128 + wc * 32 + 8 * fq;
;         const LAS float* rt = rt_.of(u.pm) + wr * 64 + fr;
; #pragma unroll
;         for (int ai = 0; ai < 2; ++ai)
; #pragma unroll
;             for (int m = 0; m < 4; ++m) { bf16_t* rowp = O + (size_t)(row0 + ai * 128 + m * 16) * FF + col0; const float r = rt[ai * 128 + m * 16];
;                 const float rl = -r * LOG2E, r2 = r * r; unsigned w[4];
; #pragma unroll
;                 for (int n = 0; n < 2; ++n)
; #pragma unroll
;                     for (int h = 0; h < 2; ++h) { const f32x2v g = {acc[ai][0][m][n][2 * h], acc[ai][0][m][n][2 * h + 1]}, uu = {acc[ai][1][m][n][2 * h], acc[ai][1][m][n][2 * h + 1]};
;                         const f32x2v t = g * rl; f32x2v d = {__builtin_amdgcn_exp2f(t.x), __builtin_amdgcn_exp2f(t.y)}; d = d + 1.0f;
;                         const f32x2v q = {__builtin_amdgcn_rcpf(d.x), __builtin_amdgcn_rcpf(d.y)}; const f32x2v o = ((g * uu) * r2) * q;
;                         w[2 * n + h] = cvt_pk2(o.x, o.y); }
;                 u32x4 wv; wv.x = w[0]; wv.y = w[1]; wv.z = w[2]; wv.w = w[3];
;                 *(u32x4*)rowp = wv; }
.LBB0_813:
	s_cmp_eq_u32 s34, s48
	s_cselect_b32 s13, s62, 0x300
	s_cmp_lg_u32 s34, s49
	s_cselect_b32 s13, s13, 0x100
	s_cmp_lg_u32 s34, s47
	s_cselect_b32 s13, s13, 0
	v_lshl_add_u32 v154, s13, 2, v148
	ds_read2_b32 v[200:201], v154 offset1:16
	ds_read2_b32 v[202:203], v154 offset0:32 offset1:48
	ds_read2_b32 v[204:205], v154 offset0:128 offset1:144
	ds_read2_b32 v[206:207], v154 offset0:160 offset1:176
	v_lshl_add_u32 v153, s34, 8, v146
	v_lshl_or_b32 v158, s64, 7, v149
	v_mov_b64_e32 v[178:179], s[40:41]
	s_mov_b32 s98, 0x1600
	v_lshlrev_b32_e32 v158, 1, v158
	v_mov_b32_e32 v159, 0
	v_mad_i64_i32 v[178:179], s[20:21], v153, s98, v[178:179]
	s_mov_b32 s98, 0x16000
	s_mov_b32 s99, 0
	s_mov_b32 s100, 0x6e000
	s_mov_b32 s101, 0
	v_lshl_add_u64 v[178:179], v[178:179], 0, v[158:159]
	s_waitcnt lgkmcnt(0)
	v_mul_f32_e32 v208, 0xbfb8aa3b, v200
	v_mul_f32_e32 v228, v200, v200
	v_mul_f32_e32 v210, 0xbfb8aa3b, v201
	v_mul_f32_e32 v230, v201, v201
	v_mul_f32_e32 v212, 0xbfb8aa3b, v202
	v_mul_f32_e32 v232, v202, v202
	v_mul_f32_e32 v214, 0xbfb8aa3b, v203
	v_mul_f32_e32 v234, v203, v203
	v_mul_f32_e32 v216, 0xbfb8aa3b, v204
	v_mul_f32_e32 v236, v204, v204
	v_mul_f32_e32 v218, 0xbfb8aa3b, v205
	v_mul_f32_e32 v238, v205, v205
	v_mul_f32_e32 v220, 0xbfb8aa3b, v206
	v_mul_f32_e32 v240, v206, v206
	v_mul_f32_e32 v222, 0xbfb8aa3b, v207
	v_mul_f32_e32 v242, v207, v207
	v_rcp_f32_e32 v228, v228
	v_rcp_f32_e32 v230, v230
	v_rcp_f32_e32 v232, v232
	v_rcp_f32_e32 v234, v234
	v_rcp_f32_e32 v236, v236
	v_rcp_f32_e32 v238, v238
	v_rcp_f32_e32 v240, v240
	v_rcp_f32_e32 v242, v242
	v_pk_mul_f32 v[154:155], v[124:125], v[208:209] op_sel_hi:[1,0]
	v_pk_mul_f32 v[156:157], v[126:127], v[208:209] op_sel_hi:[1,0]
	v_pk_mul_f32 v[158:159], v[116:117], v[208:209] op_sel_hi:[1,0]
	v_pk_mul_f32 v[160:161], v[118:119], v[208:209] op_sel_hi:[1,0]
	v_exp_f32_e32 v154, v154
	v_exp_f32_e32 v155, v155
	v_exp_f32_e32 v156, v156
	v_exp_f32_e32 v157, v157
	v_exp_f32_e32 v158, v158
	v_exp_f32_e32 v159, v159
	v_exp_f32_e32 v160, v160
	v_exp_f32_e32 v161, v161
	v_pk_mul_f32 v[162:163], v[108:109], v[210:211] op_sel_hi:[1,0]
	v_pk_mul_f32 v[164:165], v[110:111], v[210:211] op_sel_hi:[1,0]
	v_pk_mul_f32 v[166:167], v[100:101], v[210:211] op_sel_hi:[1,0]
	v_pk_mul_f32 v[168:169], v[102:103], v[210:211] op_sel_hi:[1,0]
	v_exp_f32_e32 v162, v162
	v_exp_f32_e32 v163, v163
	v_exp_f32_e32 v164, v164
	v_exp_f32_e32 v165, v165
	v_exp_f32_e32 v166, v166
	v_exp_f32_e32 v167, v167
	v_exp_f32_e32 v168, v168
	v_exp_f32_e32 v169, v169
	v_pk_mul_f32 v[120:121], v[124:125], v[120:121]
	v_pk_mul_f32 v[122:123], v[126:127], v[122:123]
	v_pk_mul_f32 v[112:113], v[116:117], v[112:113]
	v_pk_mul_f32 v[114:115], v[118:119], v[114:115]
	v_pk_fma_f32 v[154:155], v[154:155], v[228:229], v[228:229] op_sel_hi:[1,0,0]
	v_pk_fma_f32 v[156:157], v[156:157], v[228:229], v[228:229] op_sel_hi:[1,0,0]
	v_pk_fma_f32 v[158:159], v[158:159], v[228:229], v[228:229] op_sel_hi:[1,0,0]
	v_pk_fma_f32 v[160:161], v[160:161], v[228:229], v[228:229] op_sel_hi:[1,0,0]
	v_rcp_f32_e32 v154, v154
	v_rcp_f32_e32 v155, v155
	v_rcp_f32_e32 v156, v156
	v_rcp_f32_e32 v157, v157
	v_rcp_f32_e32 v158, v158
	v_rcp_f32_e32 v159, v159
	v_rcp_f32_e32 v160, v160
	v_rcp_f32_e32 v161, v161
	v_pk_mul_f32 v[170:171], v[92:93], v[212:213] op_sel_hi:[1,0]
	v_pk_mul_f32 v[172:173], v[94:95], v[212:213] op_sel_hi:[1,0]
	v_pk_mul_f32 v[174:175], v[84:85], v[212:213] op_sel_hi:[1,0]
	v_pk_mul_f32 v[176:177], v[86:87], v[212:213] op_sel_hi:[1,0]
	v_exp_f32_e32 v170, v170
	v_exp_f32_e32 v171, v171
	v_exp_f32_e32 v172, v172
	v_exp_f32_e32 v173, v173
	v_exp_f32_e32 v174, v174
	v_exp_f32_e32 v175, v175
	v_exp_f32_e32 v176, v176
	v_exp_f32_e32 v177, v177
	v_pk_mul_f32 v[104:105], v[108:109], v[104:105]
	v_pk_mul_f32 v[106:107], v[110:111], v[106:107]
	v_pk_mul_f32 v[96:97], v[100:101], v[96:97]
	v_pk_mul_f32 v[98:99], v[102:103], v[98:99]
	v_pk_fma_f32 v[162:163], v[162:163], v[230:231], v[230:231] op_sel_hi:[1,0,0]
	v_pk_fma_f32 v[164:165], v[164:165], v[230:231], v[230:231] op_sel_hi:[1,0,0]
	v_pk_fma_f32 v[166:167], v[166:167], v[230:231], v[230:231] op_sel_hi:[1,0,0]
	v_pk_fma_f32 v[168:169], v[168:169], v[230:231], v[230:231] op_sel_hi:[1,0,0]
	v_rcp_f32_e32 v162, v162
	v_rcp_f32_e32 v163, v163
	v_rcp_f32_e32 v164, v164
	v_rcp_f32_e32 v165, v165
	v_rcp_f32_e32 v166, v166
	v_rcp_f32_e32 v167, v167
	v_rcp_f32_e32 v168, v168
	v_rcp_f32_e32 v169, v169
	v_pk_mul_f32 v[120:121], v[120:121], v[154:155]
	v_pk_mul_f32 v[122:123], v[122:123], v[156:157]
	v_pk_mul_f32 v[112:113], v[112:113], v[158:159]
	v_pk_mul_f32 v[114:115], v[114:115], v[160:161]
	v_cvt_pk_bf16_f32 v154, v120, v121
	v_cvt_pk_bf16_f32 v155, v122, v123
	v_cvt_pk_bf16_f32 v156, v112, v113
	v_cvt_pk_bf16_f32 v157, v114, v115
	global_store_dwordx4 v[178:179], v[154:157], off
	v_lshl_add_u64 v[178:179], v[178:179], 0, s[98:99]
	s_nop 1
	v_pk_mul_f32 v[154:155], v[76:77], v[214:215] op_sel_hi:[1,0]
	v_pk_mul_f32 v[156:157], v[78:79], v[214:215] op_sel_hi:[1,0]
	v_pk_mul_f32 v[158:159], v[68:69], v[214:215] op_sel_hi:[1,0]
	v_pk_mul_f32 v[160:161], v[70:71], v[214:215] op_sel_hi:[1,0]
	v_exp_f32_e32 v154, v154
	v_exp_f32_e32 v155, v155
	v_exp_f32_e32 v156, v156
	v_exp_f32_e32 v157, v157
	v_exp_f32_e32 v158, v158
	v_exp_f32_e32 v159, v159
	v_exp_f32_e32 v160, v160
	v_exp_f32_e32 v161, v161
	v_pk_mul_f32 v[88:89], v[92:93], v[88:89]
	v_pk_mul_f32 v[90:91], v[94:95], v[90:91]
	v_pk_mul_f32 v[80:81], v[84:85], v[80:81]
	v_pk_mul_f32 v[82:83], v[86:87], v[82:83]
	v_pk_fma_f32 v[170:171], v[170:171], v[232:233], v[232:233] op_sel_hi:[1,0,0]
	v_pk_fma_f32 v[172:173], v[172:173], v[232:233], v[232:233] op_sel_hi:[1,0,0]
; __device__ __forceinline__ unsigned cvt_pk2(float lo, float hi) { f32x2c v = {lo, hi}; bf16x2c q = __builtin_convertvector(v, bf16x2c); return __builtin_bit_cast(unsigned, q); }
;     __device__ __forceinline__ void operator()(const f32x4 (&acc)[2][2][4][2], const pg8::Unit& u, int wr, int wc, int fr, int fq) const {
;     ...
;             for (int m = 0; m < 4; ++m) { bf16_t* rowp = O + (size_t)(row0 + ai * 128 + m * 16) * FF + col0; const float r = rt[ai * 128 + m * 16];
;                 const float rl = -r * LOG2E, r2 = r * r; unsigned w[4];
; #pragma unroll
;                 for (int n = 0; n < 2; ++n)
; #pragma unroll
;                     for (int h = 0; h < 2; ++h) { const f32x2v g = {acc[ai][0][m][n][2 * h], acc[ai][0][m][n][2 * h + 1]}, uu = {acc[ai][1][m][n][2 * h], acc[ai][1][m][n][2 * h + 1]};
;                         const f32x2v t = g * rl; f32x2v d = {__builtin_amdgcn_exp2f(t.x), __builtin_amdgcn_exp2f(t.y)}; d = d + 1.0f;
;                         const f32x2v q = {__builtin_amdgcn_rcpf(d.x), __builtin_amdgcn_rcpf(d.y)}; const f32x2v o = ((g * uu) * r2) * q;
;                         w[2 * n + h] = cvt_pk2(o.x, o.y); }
;                 u32x4 wv; wv.x = w[0]; wv.y = w[1]; wv.z = w[2]; wv.w = w[3];
;                 *(u32x4*)rowp = wv; }
	v_pk_fma_f32 v[174:175], v[174:175], v[232:233], v[232:233] op_sel_hi:[1,0,0]
	v_pk_fma_f32 v[176:177], v[176:177], v[232:233], v[232:233] op_sel_hi:[1,0,0]
	v_rcp_f32_e32 v170, v170
	v_rcp_f32_e32 v171, v171
	v_rcp_f32_e32 v172, v172
	v_rcp_f32_e32 v173, v173
	v_rcp_f32_e32 v174, v174
	v_rcp_f32_e32 v175, v175
	v_rcp_f32_e32 v176, v176
	v_rcp_f32_e32 v177, v177
	v_pk_mul_f32 v[104:105], v[104:105], v[162:163]
	v_pk_mul_f32 v[106:107], v[106:107], v[164:165]
	v_pk_mul_f32 v[96:97], v[96:97], v[166:167]
	v_pk_mul_f32 v[98:99], v[98:99], v[168:169]
	v_cvt_pk_bf16_f32 v162, v104, v105
	v_cvt_pk_bf16_f32 v163, v106, v107
	v_cvt_pk_bf16_f32 v164, v96, v97
	v_cvt_pk_bf16_f32 v165, v98, v99
	global_store_dwordx4 v[178:179], v[162:165], off
	v_lshl_add_u64 v[178:179], v[178:179], 0, s[98:99]
	s_nop 1
	v_pk_mul_f32 v[162:163], v[60:61], v[216:217] op_sel_hi:[1,0]
	v_pk_mul_f32 v[164:165], v[62:63], v[216:217] op_sel_hi:[1,0]
	v_pk_mul_f32 v[166:167], v[52:53], v[216:217] op_sel_hi:[1,0]
	v_pk_mul_f32 v[168:169], v[54:55], v[216:217] op_sel_hi:[1,0]
	v_exp_f32_e32 v162, v162
	v_exp_f32_e32 v163, v163
	v_exp_f32_e32 v164, v164
	v_exp_f32_e32 v165, v165
	v_exp_f32_e32 v166, v166
	v_exp_f32_e32 v167, v167
	v_exp_f32_e32 v168, v168
	v_exp_f32_e32 v169, v169
	v_pk_mul_f32 v[72:73], v[76:77], v[72:73]
	v_pk_mul_f32 v[74:75], v[78:79], v[74:75]
	v_pk_mul_f32 v[64:65], v[68:69], v[64:65]
	v_pk_mul_f32 v[66:67], v[70:71], v[66:67]
	v_pk_fma_f32 v[154:155], v[154:155], v[234:235], v[234:235] op_sel_hi:[1,0,0]
	v_pk_fma_f32 v[156:157], v[156:157], v[234:235], v[234:235] op_sel_hi:[1,0,0]
	v_pk_fma_f32 v[158:159], v[158:159], v[234:235], v[234:235] op_sel_hi:[1,0,0]
	v_pk_fma_f32 v[160:161], v[160:161], v[234:235], v[234:235] op_sel_hi:[1,0,0]
	v_rcp_f32_e32 v154, v154
	v_rcp_f32_e32 v155, v155
	v_rcp_f32_e32 v156, v156
	v_rcp_f32_e32 v157, v157
	v_rcp_f32_e32 v158, v158
	v_rcp_f32_e32 v159, v159
	v_rcp_f32_e32 v160, v160
	v_rcp_f32_e32 v161, v161
	v_pk_mul_f32 v[88:89], v[88:89], v[170:171]
	v_pk_mul_f32 v[90:91], v[90:91], v[172:173]
	v_pk_mul_f32 v[80:81], v[80:81], v[174:175]
	v_pk_mul_f32 v[82:83], v[82:83], v[176:177]
	v_cvt_pk_bf16_f32 v170, v88, v89
	v_cvt_pk_bf16_f32 v171, v90, v91
	v_cvt_pk_bf16_f32 v172, v80, v81
	v_cvt_pk_bf16_f32 v173, v82, v83
	global_store_dwordx4 v[178:179], v[170:173], off
	v_lshl_add_u64 v[178:179], v[178:179], 0, s[98:99]
	s_nop 1
	v_pk_mul_f32 v[170:171], v[44:45], v[218:219] op_sel_hi:[1,0]
	v_pk_mul_f32 v[172:173], v[46:47], v[218:219] op_sel_hi:[1,0]
	v_pk_mul_f32 v[174:175], v[36:37], v[218:219] op_sel_hi:[1,0]
	v_pk_mul_f32 v[176:177], v[38:39], v[218:219] op_sel_hi:[1,0]
	v_exp_f32_e32 v170, v170
	v_exp_f32_e32 v171, v171
	v_exp_f32_e32 v172, v172
	v_exp_f32_e32 v173, v173
	v_exp_f32_e32 v174, v174
	v_exp_f32_e32 v175, v175
	v_exp_f32_e32 v176, v176
	v_exp_f32_e32 v177, v177
	v_pk_mul_f32 v[56:57], v[60:61], v[56:57]
	v_pk_mul_f32 v[58:59], v[62:63], v[58:59]
	v_pk_mul_f32 v[48:49], v[52:53], v[48:49]
	v_pk_mul_f32 v[50:51], v[54:55], v[50:51]
	v_pk_fma_f32 v[162:163], v[162:163], v[236:237], v[236:237] op_sel_hi:[1,0,0]
	v_pk_fma_f32 v[164:165], v[164:165], v[236:237], v[236:237] op_sel_hi:[1,0,0]
	v_pk_fma_f32 v[166:167], v[166:167], v[236:237], v[236:237] op_sel_hi:[1,0,0]
	v_pk_fma_f32 v[168:169], v[168:169], v[236:237], v[236:237] op_sel_hi:[1,0,0]
	v_rcp_f32_e32 v162, v162
	v_rcp_f32_e32 v163, v163
	v_rcp_f32_e32 v164, v164
	v_rcp_f32_e32 v165, v165
	v_rcp_f32_e32 v166, v166
	v_rcp_f32_e32 v167, v167
	v_rcp_f32_e32 v168, v168
	v_rcp_f32_e32 v169, v169
	v_pk_mul_f32 v[72:73], v[72:73], v[154:155]
	v_pk_mul_f32 v[74:75], v[74:75], v[156:157]
	v_pk_mul_f32 v[64:65], v[64:65], v[158:159]
	v_pk_mul_f32 v[66:67], v[66:67], v[160:161]
	v_cvt_pk_bf16_f32 v154, v72, v73
	v_cvt_pk_bf16_f32 v155, v74, v75
	v_cvt_pk_bf16_f32 v156, v64, v65
	v_cvt_pk_bf16_f32 v157, v66, v67
	global_store_dwordx4 v[178:179], v[154:157], off
	v_lshl_add_u64 v[178:179], v[178:179], 0, s[100:101]
	s_nop 1
	v_pk_mul_f32 v[154:155], v[28:29], v[220:221] op_sel_hi:[1,0]
	v_pk_mul_f32 v[156:157], v[30:31], v[220:221] op_sel_hi:[1,0]
	v_pk_mul_f32 v[158:159], v[20:21], v[220:221] op_sel_hi:[1,0]
	v_pk_mul_f32 v[160:161], v[22:23], v[220:221] op_sel_hi:[1,0]
	v_exp_f32_e32 v154, v154
	v_exp_f32_e32 v155, v155
	v_exp_f32_e32 v156, v156
	v_exp_f32_e32 v157, v157
	v_exp_f32_e32 v158, v158
	v_exp_f32_e32 v159, v159
; __device__ __forceinline__ unsigned cvt_pk2(float lo, float hi) { f32x2c v = {lo, hi}; bf16x2c q = __builtin_convertvector(v, bf16x2c); return __builtin_bit_cast(unsigned, q); }
;     __device__ __forceinline__ void operator()(const f32x4 (&acc)[2][2][4][2], const pg8::Unit& u, int wr, int wc, int fr, int fq) const {
;     ...
;             for (int m = 0; m < 4; ++m) { bf16_t* rowp = O + (size_t)(row0 + ai * 128 + m * 16) * FF + col0; const float r = rt[ai * 128 + m * 16];
;                 const float rl = -r * LOG2E, r2 = r * r; unsigned w[4];
; #pragma unroll
;                 for (int n = 0; n < 2; ++n)
; #pragma unroll
;                     for (int h = 0; h < 2; ++h) { const f32x2v g = {acc[ai][0][m][n][2 * h], acc[ai][0][m][n][2 * h + 1]}, uu = {acc[ai][1][m][n][2 * h], acc[ai][1][m][n][2 * h + 1]};
;                         const f32x2v t = g * rl; f32x2v d = {__builtin_amdgcn_exp2f(t.x), __builtin_amdgcn_exp2f(t.y)}; d = d + 1.0f;
;                         const f32x2v q = {__builtin_amdgcn_rcpf(d.x), __builtin_amdgcn_rcpf(d.y)}; const f32x2v o = ((g * uu) * r2) * q;
;                         w[2 * n + h] = cvt_pk2(o.x, o.y); }
;                 u32x4 wv; wv.x = w[0]; wv.y = w[1]; wv.z = w[2]; wv.w = w[3];
;                 *(u32x4*)rowp = wv; }
	v_exp_f32_e32 v160, v160
	v_exp_f32_e32 v161, v161
	v_pk_mul_f32 v[40:41], v[44:45], v[40:41]
	v_pk_mul_f32 v[42:43], v[46:47], v[42:43]
	v_pk_mul_f32 v[32:33], v[36:37], v[32:33]
	v_pk_mul_f32 v[34:35], v[38:39], v[34:35]
	v_pk_fma_f32 v[170:171], v[170:171], v[238:239], v[238:239] op_sel_hi:[1,0,0]
	v_pk_fma_f32 v[172:173], v[172:173], v[238:239], v[238:239] op_sel_hi:[1,0,0]
	v_pk_fma_f32 v[174:175], v[174:175], v[238:239], v[238:239] op_sel_hi:[1,0,0]
	v_pk_fma_f32 v[176:177], v[176:177], v[238:239], v[238:239] op_sel_hi:[1,0,0]
	v_rcp_f32_e32 v170, v170
	v_rcp_f32_e32 v171, v171
	v_rcp_f32_e32 v172, v172
	v_rcp_f32_e32 v173, v173
	v_rcp_f32_e32 v174, v174
	v_rcp_f32_e32 v175, v175
	v_rcp_f32_e32 v176, v176
	v_rcp_f32_e32 v177, v177
	v_pk_mul_f32 v[56:57], v[56:57], v[162:163]
	v_pk_mul_f32 v[58:59], v[58:59], v[164:165]
	v_pk_mul_f32 v[48:49], v[48:49], v[166:167]
	v_pk_mul_f32 v[50:51], v[50:51], v[168:169]
	v_cvt_pk_bf16_f32 v162, v56, v57
	v_cvt_pk_bf16_f32 v163, v58, v59
	v_cvt_pk_bf16_f32 v164, v48, v49
	v_cvt_pk_bf16_f32 v165, v50, v51
	global_store_dwordx4 v[178:179], v[162:165], off
	v_lshl_add_u64 v[178:179], v[178:179], 0, s[98:99]
	s_nop 1
	v_pk_mul_f32 v[162:163], v[12:13], v[222:223] op_sel_hi:[1,0]
	v_pk_mul_f32 v[164:165], v[14:15], v[222:223] op_sel_hi:[1,0]
	v_pk_mul_f32 v[166:167], v[4:5], v[222:223] op_sel_hi:[1,0]
	v_pk_mul_f32 v[168:169], v[6:7], v[222:223] op_sel_hi:[1,0]
	v_exp_f32_e32 v162, v162
	v_exp_f32_e32 v163, v163
	v_exp_f32_e32 v164, v164
	v_exp_f32_e32 v165, v165
	v_exp_f32_e32 v166, v166
	v_exp_f32_e32 v167, v167
	v_exp_f32_e32 v168, v168
	v_exp_f32_e32 v169, v169
	v_pk_mul_f32 v[24:25], v[28:29], v[24:25]
	v_pk_mul_f32 v[26:27], v[30:31], v[26:27]
	v_pk_mul_f32 v[16:17], v[20:21], v[16:17]
	v_pk_mul_f32 v[18:19], v[22:23], v[18:19]
	v_pk_fma_f32 v[154:155], v[154:155], v[240:241], v[240:241] op_sel_hi:[1,0,0]
	v_pk_fma_f32 v[156:157], v[156:157], v[240:241], v[240:241] op_sel_hi:[1,0,0]
	v_pk_fma_f32 v[158:159], v[158:159], v[240:241], v[240:241] op_sel_hi:[1,0,0]
	v_pk_fma_f32 v[160:161], v[160:161], v[240:241], v[240:241] op_sel_hi:[1,0,0]
	v_rcp_f32_e32 v154, v154
	v_rcp_f32_e32 v155, v155
	v_rcp_f32_e32 v156, v156
	v_rcp_f32_e32 v157, v157
	v_rcp_f32_e32 v158, v158
	v_rcp_f32_e32 v159, v159
	v_rcp_f32_e32 v160, v160
	v_rcp_f32_e32 v161, v161
	v_pk_mul_f32 v[40:41], v[40:41], v[170:171]
	v_pk_mul_f32 v[42:43], v[42:43], v[172:173]
	v_pk_mul_f32 v[32:33], v[32:33], v[174:175]
	v_pk_mul_f32 v[34:35], v[34:35], v[176:177]
	v_cvt_pk_bf16_f32 v170, v40, v41
	v_cvt_pk_bf16_f32 v171, v42, v43
	v_cvt_pk_bf16_f32 v172, v32, v33
	v_cvt_pk_bf16_f32 v173, v34, v35
	global_store_dwordx4 v[178:179], v[170:173], off
	v_lshl_add_u64 v[178:179], v[178:179], 0, s[98:99]
	s_nop 1
	v_pk_mul_f32 v[8:9], v[12:13], v[8:9]
	v_pk_mul_f32 v[10:11], v[14:15], v[10:11]
	v_pk_mul_f32 v[0:1], v[4:5], v[0:1]
	v_pk_mul_f32 v[2:3], v[6:7], v[2:3]
	v_pk_fma_f32 v[162:163], v[162:163], v[242:243], v[242:243] op_sel_hi:[1,0,0]
	v_pk_fma_f32 v[164:165], v[164:165], v[242:243], v[242:243] op_sel_hi:[1,0,0]
	v_pk_fma_f32 v[166:167], v[166:167], v[242:243], v[242:243] op_sel_hi:[1,0,0]
	v_pk_fma_f32 v[168:169], v[168:169], v[242:243], v[242:243] op_sel_hi:[1,0,0]
	v_rcp_f32_e32 v162, v162
	v_rcp_f32_e32 v163, v163
	v_rcp_f32_e32 v164, v164
	v_rcp_f32_e32 v165, v165
	v_rcp_f32_e32 v166, v166
	v_rcp_f32_e32 v167, v167
	v_rcp_f32_e32 v168, v168
	v_rcp_f32_e32 v169, v169
	v_pk_mul_f32 v[24:25], v[24:25], v[154:155]
	v_pk_mul_f32 v[26:27], v[26:27], v[156:157]
	v_pk_mul_f32 v[16:17], v[16:17], v[158:159]
	v_pk_mul_f32 v[18:19], v[18:19], v[160:161]
	v_cvt_pk_bf16_f32 v154, v24, v25
	v_cvt_pk_bf16_f32 v155, v26, v27
	v_cvt_pk_bf16_f32 v156, v16, v17
	v_cvt_pk_bf16_f32 v157, v18, v19
	global_store_dwordx4 v[178:179], v[154:157], off
	v_lshl_add_u64 v[178:179], v[178:179], 0, s[98:99]
	s_nop 1
	v_pk_mul_f32 v[8:9], v[8:9], v[162:163]
	v_pk_mul_f32 v[10:11], v[10:11], v[164:165]
	v_pk_mul_f32 v[0:1], v[0:1], v[166:167]
	v_pk_mul_f32 v[2:3], v[2:3], v[168:169]
	v_cvt_pk_bf16_f32 v162, v8, v9
	v_cvt_pk_bf16_f32 v163, v10, v11
	v_cvt_pk_bf16_f32 v164, v0, v1
	v_cvt_pk_bf16_f32 v165, v2, v3
	global_store_dwordx4 v[178:179], v[162:165], off
	s_andn2_b64 vcc, exec, s[4:5]
	s_mov_b64 s[4:5], -1
	s_cbranch_vccnz .LBB0_806
	s_andn2_b64 vcc, exec, s[0:1]
	s_cbranch_vccnz .LBB0_805
	s_barrier
	s_branch .LBB0_805

; #define LAS __attribute__((address_space(3)))
; __device__ __forceinline__ unsigned cvt_pk2(float lo, float hi) { f32x2c v = {lo, hi}; bf16x2c q = __builtin_convertvector(v, bf16x2c); return __builtin_bit_cast(unsigned, q); }
;     __device__ __forceinline__ void operator()(const f32x4 (&acc)[2][2][4][2], const pg8::Unit& u, int wr, int wc, int fr, int fq) const {
;         const int row0 = u.pm * 256 + wr * 64 + fr, col0 = u.pn * 128 + wc * 32 + 8 * fq;
;         const LAS float* rt = rt_.of(u.pm) + wr * 64 + fr;
; #pragma unroll
;         for (int ai = 0; ai < 2; ++ai)
; #pragma unroll
;             for (int m = 0; m < 4; ++m) { bf16_t* rowp = O + (size_t)(row0 + ai * 128 + m * 16) * FF + col0; const float r = rt[ai * 128 + m * 16];
;                 const float rl = -r * LOG2E, r2 = r * r; unsigned w[4];
; #pragma unroll
;                 for (int n = 0; n < 2; ++n)
; #pragma unroll
;                     for (int h = 0; h < 2; ++h) { const f32x2v g = {acc[ai][0][m][n][2 * h], acc[ai][0][m][n][2 * h + 1]}, uu = {acc[ai][1][m][n][2 * h], acc[ai][1][m][n][2 * h + 1]};
;                         const f32x2v t = g * rl; f32x2v d = {__builtin_amdgcn_exp2f(t.x), __builtin_amdgcn_exp2f(t.y)}; d = d + 1.0f;
;                         const f32x2v q = {__builtin_amdgcn_rcpf(d.x), __builtin_amdgcn_rcpf(d.y)}; const f32x2v o = ((g * uu) * r2) * q;
;                         w[2 * n + h] = cvt_pk2(o.x, o.y); }
;                 u32x4 wv; wv.x = w[0]; wv.y = w[1]; wv.z = w[2]; wv.w = w[3];
;                 *(u32x4*)rowp = wv; }
.LBB0_1743:
	s_cmp_eq_u32 s34, s45
	s_cselect_b32 s13, s60, 0x300
	s_cmp_lg_u32 s34, s46
	s_cselect_b32 s13, s13, 0x100
	s_cmp_lg_u32 s34, s47
	s_cselect_b32 s13, s13, 0
	v_lshl_add_u32 v154, s13, 2, v148
	ds_read2_b32 v[200:201], v154 offset1:16
	ds_read2_b32 v[202:203], v154 offset0:32 offset1:48
	ds_read2_b32 v[204:205], v154 offset0:128 offset1:144
	ds_read2_b32 v[206:207], v154 offset0:160 offset1:176
	v_lshl_add_u32 v153, s34, 8, v146
	v_lshl_or_b32 v158, s62, 7, v149
	v_mov_b64_e32 v[178:179], s[40:41]
	s_mov_b32 s98, 0x1600
	v_lshlrev_b32_e32 v158, 1, v158
	v_mov_b32_e32 v159, 0
	v_mad_i64_i32 v[178:179], s[20:21], v153, s98, v[178:179]
	s_mov_b32 s98, 0x16000
	s_mov_b32 s99, 0
	s_mov_b32 s100, 0x6e000
	s_mov_b32 s101, 0
	v_lshl_add_u64 v[178:179], v[178:179], 0, v[158:159]
	s_waitcnt lgkmcnt(0)
	v_mul_f32_e32 v208, 0xbfb8aa3b, v200
	v_mul_f32_e32 v228, v200, v200
	v_mul_f32_e32 v210, 0xbfb8aa3b, v201
	v_mul_f32_e32 v230, v201, v201
	v_mul_f32_e32 v212, 0xbfb8aa3b, v202
	v_mul_f32_e32 v232, v202, v202
	v_mul_f32_e32 v214, 0xbfb8aa3b, v203
	v_mul_f32_e32 v234, v203, v203
	v_mul_f32_e32 v216, 0xbfb8aa3b, v204
	v_mul_f32_e32 v236, v204, v204
	v_mul_f32_e32 v218, 0xbfb8aa3b, v205
	v_mul_f32_e32 v238, v205, v205
	v_mul_f32_e32 v220, 0xbfb8aa3b, v206
	v_mul_f32_e32 v240, v206, v206
	v_mul_f32_e32 v222, 0xbfb8aa3b, v207
	v_mul_f32_e32 v242, v207, v207
	v_rcp_f32_e32 v228, v228
	v_rcp_f32_e32 v230, v230
	v_rcp_f32_e32 v232, v232
	v_rcp_f32_e32 v234, v234
	v_rcp_f32_e32 v236, v236
	v_rcp_f32_e32 v238, v238
	v_rcp_f32_e32 v240, v240
	v_rcp_f32_e32 v242, v242
	v_pk_mul_f32 v[154:155], v[124:125], v[208:209] op_sel_hi:[1,0]
	v_pk_mul_f32 v[156:157], v[126:127], v[208:209] op_sel_hi:[1,0]
	v_pk_mul_f32 v[158:159], v[116:117], v[208:209] op_sel_hi:[1,0]
	v_pk_mul_f32 v[160:161], v[118:119], v[208:209] op_sel_hi:[1,0]
	v_exp_f32_e32 v154, v154
	v_exp_f32_e32 v155, v155
	v_exp_f32_e32 v156, v156
	v_exp_f32_e32 v157, v157
	v_exp_f32_e32 v158, v158
	v_exp_f32_e32 v159, v159
	v_exp_f32_e32 v160, v160
	v_exp_f32_e32 v161, v161
	v_pk_mul_f32 v[162:163], v[108:109], v[210:211] op_sel_hi:[1,0]
	v_pk_mul_f32 v[164:165], v[110:111], v[210:211] op_sel_hi:[1,0]
	v_pk_mul_f32 v[166:167], v[100:101], v[210:211] op_sel_hi:[1,0]
	v_pk_mul_f32 v[168:169], v[102:103], v[210:211] op_sel_hi:[1,0]
	v_exp_f32_e32 v162, v162
	v_exp_f32_e32 v163, v163
	v_exp_f32_e32 v164, v164
	v_exp_f32_e32 v165, v165
	v_exp_f32_e32 v166, v166
	v_exp_f32_e32 v167, v167
	v_exp_f32_e32 v168, v168
	v_exp_f32_e32 v169, v169
	v_pk_mul_f32 v[120:121], v[124:125], v[120:121]
	v_pk_mul_f32 v[122:123], v[126:127], v[122:123]
	v_pk_mul_f32 v[112:113], v[116:117], v[112:113]
	v_pk_mul_f32 v[114:115], v[118:119], v[114:115]
	v_pk_fma_f32 v[154:155], v[154:155], v[228:229], v[228:229] op_sel_hi:[1,0,0]
	v_pk_fma_f32 v[156:157], v[156:157], v[228:229], v[228:229] op_sel_hi:[1,0,0]
	v_pk_fma_f32 v[158:159], v[158:159], v[228:229], v[228:229] op_sel_hi:[1,0,0]
	v_pk_fma_f32 v[160:161], v[160:161], v[228:229], v[228:229] op_sel_hi:[1,0,0]
	v_rcp_f32_e32 v154, v154
	v_rcp_f32_e32 v155, v155
	v_rcp_f32_e32 v156, v156
	v_rcp_f32_e32 v157, v157
	v_rcp_f32_e32 v158, v158
	v_rcp_f32_e32 v159, v159
	v_rcp_f32_e32 v160, v160
	v_rcp_f32_e32 v161, v161
	v_pk_mul_f32 v[170:171], v[92:93], v[212:213] op_sel_hi:[1,0]
	v_pk_mul_f32 v[172:173], v[94:95], v[212:213] op_sel_hi:[1,0]
	v_pk_mul_f32 v[174:175], v[84:85], v[212:213] op_sel_hi:[1,0]
	v_pk_mul_f32 v[176:177], v[86:87], v[212:213] op_sel_hi:[1,0]
	v_exp_f32_e32 v170, v170
	v_exp_f32_e32 v171, v171
	v_exp_f32_e32 v172, v172
	v_exp_f32_e32 v173, v173
	v_exp_f32_e32 v174, v174
	v_exp_f32_e32 v175, v175
	v_exp_f32_e32 v176, v176
	v_exp_f32_e32 v177, v177
	v_pk_mul_f32 v[104:105], v[108:109], v[104:105]
	v_pk_mul_f32 v[106:107], v[110:111], v[106:107]
	v_pk_mul_f32 v[96:97], v[100:101], v[96:97]
	v_pk_mul_f32 v[98:99], v[102:103], v[98:99]
	v_pk_fma_f32 v[162:163], v[162:163], v[230:231], v[230:231] op_sel_hi:[1,0,0]
	v_pk_fma_f32 v[164:165], v[164:165], v[230:231], v[230:231] op_sel_hi:[1,0,0]
	v_pk_fma_f32 v[166:167], v[166:167], v[230:231], v[230:231] op_sel_hi:[1,0,0]
	v_pk_fma_f32 v[168:169], v[168:169], v[230:231], v[230:231] op_sel_hi:[1,0,0]
	v_rcp_f32_e32 v162, v162
	v_rcp_f32_e32 v163, v163
	v_rcp_f32_e32 v164, v164
	v_rcp_f32_e32 v165, v165
	v_rcp_f32_e32 v166, v166
	v_rcp_f32_e32 v167, v167
	v_rcp_f32_e32 v168, v168
	v_rcp_f32_e32 v169, v169
	v_pk_mul_f32 v[120:121], v[120:121], v[154:155]
	v_pk_mul_f32 v[122:123], v[122:123], v[156:157]
	v_pk_mul_f32 v[112:113], v[112:113], v[158:159]
	v_pk_mul_f32 v[114:115], v[114:115], v[160:161]
	v_cvt_pk_bf16_f32 v154, v120, v121
	v_cvt_pk_bf16_f32 v155, v122, v123
	v_cvt_pk_bf16_f32 v156, v112, v113
	v_cvt_pk_bf16_f32 v157, v114, v115
	global_store_dwordx4 v[178:179], v[154:157], off
	v_lshl_add_u64 v[178:179], v[178:179], 0, s[98:99]
	s_nop 1
	v_pk_mul_f32 v[154:155], v[76:77], v[214:215] op_sel_hi:[1,0]
	v_pk_mul_f32 v[156:157], v[78:79], v[214:215] op_sel_hi:[1,0]
	v_pk_mul_f32 v[158:159], v[68:69], v[214:215] op_sel_hi:[1,0]
	v_pk_mul_f32 v[160:161], v[70:71], v[214:215] op_sel_hi:[1,0]
	v_exp_f32_e32 v154, v154
	v_exp_f32_e32 v155, v155
	v_exp_f32_e32 v156, v156
	v_exp_f32_e32 v157, v157
	v_exp_f32_e32 v158, v158
	v_exp_f32_e32 v159, v159
	v_exp_f32_e32 v160, v160
	v_exp_f32_e32 v161, v161
	v_pk_mul_f32 v[88:89], v[92:93], v[88:89]
	v_pk_mul_f32 v[90:91], v[94:95], v[90:91]
	v_pk_mul_f32 v[80:81], v[84:85], v[80:81]
	v_pk_mul_f32 v[82:83], v[86:87], v[82:83]
	v_pk_fma_f32 v[170:171], v[170:171], v[232:233], v[232:233] op_sel_hi:[1,0,0]
	v_pk_fma_f32 v[172:173], v[172:173], v[232:233], v[232:233] op_sel_hi:[1,0,0]
; __device__ __forceinline__ unsigned cvt_pk2(float lo, float hi) { f32x2c v = {lo, hi}; bf16x2c q = __builtin_convertvector(v, bf16x2c); return __builtin_bit_cast(unsigned, q); }
;     __device__ __forceinline__ void operator()(const f32x4 (&acc)[2][2][4][2], const pg8::Unit& u, int wr, int wc, int fr, int fq) const {
;     ...
;             for (int m = 0; m < 4; ++m) { bf16_t* rowp = O + (size_t)(row0 + ai * 128 + m * 16) * FF + col0; const float r = rt[ai * 128 + m * 16];
;                 const float rl = -r * LOG2E, r2 = r * r; unsigned w[4];
; #pragma unroll
;                 for (int n = 0; n < 2; ++n)
; #pragma unroll
;                     for (int h = 0; h < 2; ++h) { const f32x2v g = {acc[ai][0][m][n][2 * h], acc[ai][0][m][n][2 * h + 1]}, uu = {acc[ai][1][m][n][2 * h], acc[ai][1][m][n][2 * h + 1]};
;                         const f32x2v t = g * rl; f32x2v d = {__builtin_amdgcn_exp2f(t.x), __builtin_amdgcn_exp2f(t.y)}; d = d + 1.0f;
;                         const f32x2v q = {__builtin_amdgcn_rcpf(d.x), __builtin_amdgcn_rcpf(d.y)}; const f32x2v o = ((g * uu) * r2) * q;
;                         w[2 * n + h] = cvt_pk2(o.x, o.y); }
;                 u32x4 wv; wv.x = w[0]; wv.y = w[1]; wv.z = w[2]; wv.w = w[3];
;                 *(u32x4*)rowp = wv; }
	v_pk_fma_f32 v[174:175], v[174:175], v[232:233], v[232:233] op_sel_hi:[1,0,0]
	v_pk_fma_f32 v[176:177], v[176:177], v[232:233], v[232:233] op_sel_hi:[1,0,0]
	v_rcp_f32_e32 v170, v170
	v_rcp_f32_e32 v171, v171
	v_rcp_f32_e32 v172, v172
	v_rcp_f32_e32 v173, v173
	v_rcp_f32_e32 v174, v174
	v_rcp_f32_e32 v175, v175
	v_rcp_f32_e32 v176, v176
	v_rcp_f32_e32 v177, v177
	v_pk_mul_f32 v[104:105], v[104:105], v[162:163]
	v_pk_mul_f32 v[106:107], v[106:107], v[164:165]
	v_pk_mul_f32 v[96:97], v[96:97], v[166:167]
	v_pk_mul_f32 v[98:99], v[98:99], v[168:169]
	v_cvt_pk_bf16_f32 v162, v104, v105
	v_cvt_pk_bf16_f32 v163, v106, v107
	v_cvt_pk_bf16_f32 v164, v96, v97
	v_cvt_pk_bf16_f32 v165, v98, v99
	global_store_dwordx4 v[178:179], v[162:165], off
	v_lshl_add_u64 v[178:179], v[178:179], 0, s[98:99]
	s_nop 1
	v_pk_mul_f32 v[162:163], v[60:61], v[216:217] op_sel_hi:[1,0]
	v_pk_mul_f32 v[164:165], v[62:63], v[216:217] op_sel_hi:[1,0]
	v_pk_mul_f32 v[166:167], v[52:53], v[216:217] op_sel_hi:[1,0]
	v_pk_mul_f32 v[168:169], v[54:55], v[216:217] op_sel_hi:[1,0]
	v_exp_f32_e32 v162, v162
	v_exp_f32_e32 v163, v163
	v_exp_f32_e32 v164, v164
	v_exp_f32_e32 v165, v165
	v_exp_f32_e32 v166, v166
	v_exp_f32_e32 v167, v167
	v_exp_f32_e32 v168, v168
	v_exp_f32_e32 v169, v169
	v_pk_mul_f32 v[72:73], v[76:77], v[72:73]
	v_pk_mul_f32 v[74:75], v[78:79], v[74:75]
	v_pk_mul_f32 v[64:65], v[68:69], v[64:65]
	v_pk_mul_f32 v[66:67], v[70:71], v[66:67]
	v_pk_fma_f32 v[154:155], v[154:155], v[234:235], v[234:235] op_sel_hi:[1,0,0]
	v_pk_fma_f32 v[156:157], v[156:157], v[234:235], v[234:235] op_sel_hi:[1,0,0]
	v_pk_fma_f32 v[158:159], v[158:159], v[234:235], v[234:235] op_sel_hi:[1,0,0]
	v_pk_fma_f32 v[160:161], v[160:161], v[234:235], v[234:235] op_sel_hi:[1,0,0]
	v_rcp_f32_e32 v154, v154
	v_rcp_f32_e32 v155, v155
	v_rcp_f32_e32 v156, v156
	v_rcp_f32_e32 v157, v157
	v_rcp_f32_e32 v158, v158
	v_rcp_f32_e32 v159, v159
	v_rcp_f32_e32 v160, v160
	v_rcp_f32_e32 v161, v161
	v_pk_mul_f32 v[88:89], v[88:89], v[170:171]
	v_pk_mul_f32 v[90:91], v[90:91], v[172:173]
	v_pk_mul_f32 v[80:81], v[80:81], v[174:175]
	v_pk_mul_f32 v[82:83], v[82:83], v[176:177]
	v_cvt_pk_bf16_f32 v170, v88, v89
	v_cvt_pk_bf16_f32 v171, v90, v91
	v_cvt_pk_bf16_f32 v172, v80, v81
	v_cvt_pk_bf16_f32 v173, v82, v83
	global_store_dwordx4 v[178:179], v[170:173], off
	v_lshl_add_u64 v[178:179], v[178:179], 0, s[98:99]
	s_nop 1
	v_pk_mul_f32 v[170:171], v[44:45], v[218:219] op_sel_hi:[1,0]
	v_pk_mul_f32 v[172:173], v[46:47], v[218:219] op_sel_hi:[1,0]
	v_pk_mul_f32 v[174:175], v[36:37], v[218:219] op_sel_hi:[1,0]
	v_pk_mul_f32 v[176:177], v[38:39], v[218:219] op_sel_hi:[1,0]
	v_exp_f32_e32 v170, v170
	v_exp_f32_e32 v171, v171
	v_exp_f32_e32 v172, v172
	v_exp_f32_e32 v173, v173
	v_exp_f32_e32 v174, v174
	v_exp_f32_e32 v175, v175
	v_exp_f32_e32 v176, v176
	v_exp_f32_e32 v177, v177
	v_pk_mul_f32 v[56:57], v[60:61], v[56:57]
	v_pk_mul_f32 v[58:59], v[62:63], v[58:59]
	v_pk_mul_f32 v[48:49], v[52:53], v[48:49]
	v_pk_mul_f32 v[50:51], v[54:55], v[50:51]
	v_pk_fma_f32 v[162:163], v[162:163], v[236:237], v[236:237] op_sel_hi:[1,0,0]
	v_pk_fma_f32 v[164:165], v[164:165], v[236:237], v[236:237] op_sel_hi:[1,0,0]
	v_pk_fma_f32 v[166:167], v[166:167], v[236:237], v[236:237] op_sel_hi:[1,0,0]
	v_pk_fma_f32 v[168:169], v[168:169], v[236:237], v[236:237] op_sel_hi:[1,0,0]
	v_rcp_f32_e32 v162, v162
	v_rcp_f32_e32 v163, v163
	v_rcp_f32_e32 v164, v164
	v_rcp_f32_e32 v165, v165
	v_rcp_f32_e32 v166, v166
	v_rcp_f32_e32 v167, v167
	v_rcp_f32_e32 v168, v168
	v_rcp_f32_e32 v169, v169
	v_pk_mul_f32 v[72:73], v[72:73], v[154:155]
	v_pk_mul_f32 v[74:75], v[74:75], v[156:157]
	v_pk_mul_f32 v[64:65], v[64:65], v[158:159]
	v_pk_mul_f32 v[66:67], v[66:67], v[160:161]
	v_cvt_pk_bf16_f32 v154, v72, v73
	v_cvt_pk_bf16_f32 v155, v74, v75
	v_cvt_pk_bf16_f32 v156, v64, v65
	v_cvt_pk_bf16_f32 v157, v66, v67
	global_store_dwordx4 v[178:179], v[154:157], off
	v_lshl_add_u64 v[178:179], v[178:179], 0, s[100:101]
	s_nop 1
	v_pk_mul_f32 v[154:155], v[28:29], v[220:221] op_sel_hi:[1,0]
	v_pk_mul_f32 v[156:157], v[30:31], v[220:221] op_sel_hi:[1,0]
	v_pk_mul_f32 v[158:159], v[20:21], v[220:221] op_sel_hi:[1,0]
	v_pk_mul_f32 v[160:161], v[22:23], v[220:221] op_sel_hi:[1,0]
	v_exp_f32_e32 v154, v154
	v_exp_f32_e32 v155, v155
	v_exp_f32_e32 v156, v156
	v_exp_f32_e32 v157, v157
	v_exp_f32_e32 v158, v158
	v_exp_f32_e32 v159, v159
; __device__ __forceinline__ unsigned cvt_pk2(float lo, float hi) { f32x2c v = {lo, hi}; bf16x2c q = __builtin_convertvector(v, bf16x2c); return __builtin_bit_cast(unsigned, q); }
;     __device__ __forceinline__ void operator()(const f32x4 (&acc)[2][2][4][2], const pg8::Unit& u, int wr, int wc, int fr, int fq) const {
;     ...
;             for (int m = 0; m < 4; ++m) { bf16_t* rowp = O + (size_t)(row0 + ai * 128 + m * 16) * FF + col0; const float r = rt[ai * 128 + m * 16];
;                 const float rl = -r * LOG2E, r2 = r * r; unsigned w[4];
; #pragma unroll
;                 for (int n = 0; n < 2; ++n)
; #pragma unroll
;                     for (int h = 0; h < 2; ++h) { const f32x2v g = {acc[ai][0][m][n][2 * h], acc[ai][0][m][n][2 * h + 1]}, uu = {acc[ai][1][m][n][2 * h], acc[ai][1][m][n][2 * h + 1]};
;                         const f32x2v t = g * rl; f32x2v d = {__builtin_amdgcn_exp2f(t.x), __builtin_amdgcn_exp2f(t.y)}; d = d + 1.0f;
;                         const f32x2v q = {__builtin_amdgcn_rcpf(d.x), __builtin_amdgcn_rcpf(d.y)}; const f32x2v o = ((g * uu) * r2) * q;
;                         w[2 * n + h] = cvt_pk2(o.x, o.y); }
;                 u32x4 wv; wv.x = w[0]; wv.y = w[1]; wv.z = w[2]; wv.w = w[3];
;                 *(u32x4*)rowp = wv; }
	v_exp_f32_e32 v160, v160
	v_exp_f32_e32 v161, v161
	v_pk_mul_f32 v[40:41], v[44:45], v[40:41]
	v_pk_mul_f32 v[42:43], v[46:47], v[42:43]
	v_pk_mul_f32 v[32:33], v[36:37], v[32:33]
	v_pk_mul_f32 v[34:35], v[38:39], v[34:35]
	v_pk_fma_f32 v[170:171], v[170:171], v[238:239], v[238:239] op_sel_hi:[1,0,0]
	v_pk_fma_f32 v[172:173], v[172:173], v[238:239], v[238:239] op_sel_hi:[1,0,0]
	v_pk_fma_f32 v[174:175], v[174:175], v[238:239], v[238:239] op_sel_hi:[1,0,0]
	v_pk_fma_f32 v[176:177], v[176:177], v[238:239], v[238:239] op_sel_hi:[1,0,0]
	v_rcp_f32_e32 v170, v170
	v_rcp_f32_e32 v171, v171
	v_rcp_f32_e32 v172, v172
	v_rcp_f32_e32 v173, v173
	v_rcp_f32_e32 v174, v174
	v_rcp_f32_e32 v175, v175
	v_rcp_f32_e32 v176, v176
	v_rcp_f32_e32 v177, v177
	v_pk_mul_f32 v[56:57], v[56:57], v[162:163]
	v_pk_mul_f32 v[58:59], v[58:59], v[164:165]
	v_pk_mul_f32 v[48:49], v[48:49], v[166:167]
	v_pk_mul_f32 v[50:51], v[50:51], v[168:169]
	v_cvt_pk_bf16_f32 v162, v56, v57
	v_cvt_pk_bf16_f32 v163, v58, v59
	v_cvt_pk_bf16_f32 v164, v48, v49
	v_cvt_pk_bf16_f32 v165, v50, v51
	global_store_dwordx4 v[178:179], v[162:165], off
	v_lshl_add_u64 v[178:179], v[178:179], 0, s[98:99]
	s_nop 1
	v_pk_mul_f32 v[162:163], v[12:13], v[222:223] op_sel_hi:[1,0]
	v_pk_mul_f32 v[164:165], v[14:15], v[222:223] op_sel_hi:[1,0]
	v_pk_mul_f32 v[166:167], v[4:5], v[222:223] op_sel_hi:[1,0]
	v_pk_mul_f32 v[168:169], v[6:7], v[222:223] op_sel_hi:[1,0]
	v_exp_f32_e32 v162, v162
	v_exp_f32_e32 v163, v163
	v_exp_f32_e32 v164, v164
	v_exp_f32_e32 v165, v165
	v_exp_f32_e32 v166, v166
	v_exp_f32_e32 v167, v167
	v_exp_f32_e32 v168, v168
	v_exp_f32_e32 v169, v169
	v_pk_mul_f32 v[24:25], v[28:29], v[24:25]
	v_pk_mul_f32 v[26:27], v[30:31], v[26:27]
	v_pk_mul_f32 v[16:17], v[20:21], v[16:17]
	v_pk_mul_f32 v[18:19], v[22:23], v[18:19]
	v_pk_fma_f32 v[154:155], v[154:155], v[240:241], v[240:241] op_sel_hi:[1,0,0]
	v_pk_fma_f32 v[156:157], v[156:157], v[240:241], v[240:241] op_sel_hi:[1,0,0]
	v_pk_fma_f32 v[158:159], v[158:159], v[240:241], v[240:241] op_sel_hi:[1,0,0]
	v_pk_fma_f32 v[160:161], v[160:161], v[240:241], v[240:241] op_sel_hi:[1,0,0]
	v_rcp_f32_e32 v154, v154
	v_rcp_f32_e32 v155, v155
	v_rcp_f32_e32 v156, v156
	v_rcp_f32_e32 v157, v157
	v_rcp_f32_e32 v158, v158
	v_rcp_f32_e32 v159, v159
	v_rcp_f32_e32 v160, v160
	v_rcp_f32_e32 v161, v161
	v_pk_mul_f32 v[40:41], v[40:41], v[170:171]
	v_pk_mul_f32 v[42:43], v[42:43], v[172:173]
	v_pk_mul_f32 v[32:33], v[32:33], v[174:175]
	v_pk_mul_f32 v[34:35], v[34:35], v[176:177]
	v_cvt_pk_bf16_f32 v170, v40, v41
	v_cvt_pk_bf16_f32 v171, v42, v43
	v_cvt_pk_bf16_f32 v172, v32, v33
	v_cvt_pk_bf16_f32 v173, v34, v35
	global_store_dwordx4 v[178:179], v[170:173], off
	v_lshl_add_u64 v[178:179], v[178:179], 0, s[98:99]
	s_nop 1
	v_pk_mul_f32 v[8:9], v[12:13], v[8:9]
	v_pk_mul_f32 v[10:11], v[14:15], v[10:11]
	v_pk_mul_f32 v[0:1], v[4:5], v[0:1]
	v_pk_mul_f32 v[2:3], v[6:7], v[2:3]
	v_pk_fma_f32 v[162:163], v[162:163], v[242:243], v[242:243] op_sel_hi:[1,0,0]
	v_pk_fma_f32 v[164:165], v[164:165], v[242:243], v[242:243] op_sel_hi:[1,0,0]
	v_pk_fma_f32 v[166:167], v[166:167], v[242:243], v[242:243] op_sel_hi:[1,0,0]
	v_pk_fma_f32 v[168:169], v[168:169], v[242:243], v[242:243] op_sel_hi:[1,0,0]
	v_rcp_f32_e32 v162, v162
	v_rcp_f32_e32 v163, v163
	v_rcp_f32_e32 v164, v164
	v_rcp_f32_e32 v165, v165
	v_rcp_f32_e32 v166, v166
	v_rcp_f32_e32 v167, v167
	v_rcp_f32_e32 v168, v168
	v_rcp_f32_e32 v169, v169
	v_pk_mul_f32 v[24:25], v[24:25], v[154:155]
	v_pk_mul_f32 v[26:27], v[26:27], v[156:157]
	v_pk_mul_f32 v[16:17], v[16:17], v[158:159]
	v_pk_mul_f32 v[18:19], v[18:19], v[160:161]
	v_cvt_pk_bf16_f32 v154, v24, v25
	v_cvt_pk_bf16_f32 v155, v26, v27
	v_cvt_pk_bf16_f32 v156, v16, v17
	v_cvt_pk_bf16_f32 v157, v18, v19
	global_store_dwordx4 v[178:179], v[154:157], off
	v_lshl_add_u64 v[178:179], v[178:179], 0, s[98:99]
	s_nop 1
	v_pk_mul_f32 v[8:9], v[8:9], v[162:163]
	v_pk_mul_f32 v[10:11], v[10:11], v[164:165]
	v_pk_mul_f32 v[0:1], v[0:1], v[166:167]
	v_pk_mul_f32 v[2:3], v[2:3], v[168:169]
	v_cvt_pk_bf16_f32 v162, v8, v9
	v_cvt_pk_bf16_f32 v163, v10, v11
	v_cvt_pk_bf16_f32 v164, v0, v1
	v_cvt_pk_bf16_f32 v165, v2, v3
	global_store_dwordx4 v[178:179], v[162:165], off
	s_andn2_b64 vcc, exec, s[4:5]
	s_mov_b64 s[4:5], -1
	s_cbranch_vccnz .LBB0_1736
	s_andn2_b64 vcc, exec, s[0:1]
	s_cbranch_vccnz .LBB0_1735
	s_barrier
	s_branch .LBB0_1735
